# attention instance 2: the 5 early V-fragment LDS reads now fill the 9-slot MFMA->VALU hazard pad after the QK MFMAs (s_nop 8 removed)
# baseline (speedup 1.0000x reference)
.LBB0_619:
	s_mul_i32 s10, s65, 0x2200
	v_add_u32_e32 v232, s10, v133
	v_add_u32_e32 v233, 0x7000, v232
	v_add_u32_e32 v232, 0x6000, v232
	ds_read2_b64 v[212:215], v232 offset1:2
	ds_read2_b64 v[216:219], v232 offset0:4 offset1:6
	ds_read2_b64 v[220:223], v233 offset0:32 offset1:34
	ds_read2_b64 v[224:227], v233 offset0:36 offset1:38
	ds_read2_b64 v[228:231], v232 offset0:8 offset1:10
	v_max3_f32 v145, v49, v65, v64
	v_max_f32_e32 v145, v145, v48
	v_max3_f32 v147, v66, v50, v67
	v_max3_f32 v145, v145, v147, v51
	v_max3_f32 v147, v68, v52, v69
	v_max3_f32 v145, v145, v147, v53
	v_max3_f32 v147, v70, v54, v71
	v_max3_f32 v145, v145, v147, v55
	v_max3_f32 v147, v72, v56, v73
	v_max3_f32 v145, v145, v147, v57
	v_max3_f32 v147, v74, v58, v75
	v_max3_f32 v145, v145, v147, v59
	v_max3_f32 v147, v76, v60, v77
	v_max3_f32 v145, v145, v147, v61
	v_max3_f32 v147, v78, v62, v79
	v_max3_f32 v145, v145, v147, v63
	v_mov_b32_e32 v147, v145
	s_nop 1
	v_permlane32_swap_b32_e32 v145, v147
	s_cmp_eq_u32 s63, 1
	s_cselect_b64 s[10:11], -1, 0
	s_cmp_lg_u32 s63, 1
	v_max_f32_e32 v145, v145, v147
	s_cbranch_scc0 .LBB0_632
	v_cmp_lt_f32_e32 vcc, s56, v145
	s_mov_b64 s[36:37], 0
	s_mov_b64 s[28:29], 0
	s_cbranch_vccz .LBB0_628
	v_max_f32_e32 v147, v145, v145
	v_max_f32_e32 v176, 0, v147
	s_mov_b64 s[28:29], -1

.LBB0_628:
	v_exp_f32_e32 v176, v64
	v_exp_f32_e32 v177, v65
	v_exp_f32_e32 v180, v48
	v_exp_f32_e32 v181, v49
	v_exp_f32_e32 v178, v66
	v_exp_f32_e32 v179, v67
	v_exp_f32_e32 v186, v50
	v_exp_f32_e32 v187, v51
	v_exp_f32_e32 v184, v68
	v_exp_f32_e32 v185, v69
	v_pk_add_f32 v[48:49], v[180:181], v[176:177]
	v_exp_f32_e32 v188, v52
	v_exp_f32_e32 v189, v53
	v_pk_add_f32 v[48:49], v[178:179], v[48:49]
	v_exp_f32_e32 v192, v70
	v_exp_f32_e32 v193, v71
	v_pk_add_f32 v[48:49], v[186:187], v[48:49]
	v_exp_f32_e32 v194, v54
	v_exp_f32_e32 v195, v55
	v_pk_add_f32 v[48:49], v[184:185], v[48:49]
	v_exp_f32_e32 v196, v72
	v_exp_f32_e32 v197, v73
	v_pk_add_f32 v[48:49], v[188:189], v[48:49]
	v_exp_f32_e32 v198, v56
	v_exp_f32_e32 v199, v57
	v_pk_add_f32 v[48:49], v[192:193], v[48:49]
	v_exp_f32_e32 v200, v74
	v_exp_f32_e32 v201, v75
	v_pk_add_f32 v[48:49], v[194:195], v[48:49]
	v_exp_f32_e32 v202, v58
	v_exp_f32_e32 v203, v59
	v_pk_add_f32 v[48:49], v[196:197], v[48:49]
	v_exp_f32_e32 v204, v76
	v_exp_f32_e32 v205, v77
	v_pk_add_f32 v[48:49], v[198:199], v[48:49]
	v_exp_f32_e32 v206, v60
	v_exp_f32_e32 v207, v61
	v_pk_add_f32 v[48:49], v[200:201], v[48:49]
	v_exp_f32_e32 v208, v78
	v_exp_f32_e32 v209, v79
	v_pk_add_f32 v[48:49], v[202:203], v[48:49]
	v_exp_f32_e32 v210, v62
	v_exp_f32_e32 v211, v63
	v_pk_add_f32 v[48:49], v[204:205], v[48:49]
	s_mul_i32 s10, s65, 0x2200
	v_pk_add_f32 v[48:49], v[206:207], v[48:49]
	v_add_u32_e32 v56, s10, v133
	v_pk_add_f32 v[48:49], v[208:209], v[48:49]
	v_add_u32_e32 v72, 0x6000, v56
	v_pk_add_f32 v[48:49], v[210:211], v[48:49]
	v_add_u32_e32 v76, 0x7000, v56
	v_pk_add_f32 v[48:49], v[48:49], v[48:49] op_sel:[0,1] op_sel_hi:[1,0]
	v_cvt_pk_bf16_f32 v176, v176, v177
	v_mov_b32_e32 v49, v48
	s_nop 1
	v_permlane32_swap_b32_e32 v48, v49
	v_add_f32_e32 v145, v48, v49
	ds_read2_b64 v[68:71], v76 offset0:40 offset1:42
	ds_read2_b64 v[72:75], v72 offset0:12 offset1:14
	ds_read2_b64 v[76:79], v76 offset0:44 offset1:46
	v_cvt_pk_bf16_f32 v177, v178, v179
	v_cvt_pk_bf16_f32 v178, v184, v185
	v_cvt_pk_bf16_f32 v179, v192, v193
	v_cvt_pk_bf16_f32 v184, v180, v181
	v_cvt_pk_bf16_f32 v185, v186, v187
	v_cvt_pk_bf16_f32 v186, v188, v189
	v_cvt_pk_bf16_f32 v187, v194, v195
	v_cvt_pk_bf16_f32 v192, v196, v197
	v_cvt_pk_bf16_f32 v193, v200, v201
	v_cvt_pk_bf16_f32 v194, v204, v205
	v_cvt_pk_bf16_f32 v195, v208, v209
	v_cvt_pk_bf16_f32 v196, v198, v199
	v_cvt_pk_bf16_f32 v197, v202, v203
	v_cvt_pk_bf16_f32 v198, v206, v207
	v_cvt_pk_bf16_f32 v199, v210, v211
	s_setprio 1
	s_waitcnt lgkmcnt(7)
	v_mfma_f32_32x32x16_bf16 v[0:15], v[176:179], v[212:215], v[0:15]
	v_add_f32_e32 v141, v141, v145
	s_waitcnt lgkmcnt(5)
	v_mfma_f32_32x32x16_bf16 v[16:31], v[176:179], v[220:223], v[16:31]
	v_mfma_f32_32x32x16_bf16 v[0:15], v[192:195], v[216:219], v[0:15]
	s_waitcnt lgkmcnt(4)
	v_mfma_f32_32x32x16_bf16 v[16:31], v[192:195], v[224:227], v[16:31]
	s_waitcnt lgkmcnt(3)
	v_mfma_f32_32x32x16_bf16 v[0:15], v[184:187], v[228:231], v[0:15]
	s_waitcnt lgkmcnt(2)
	v_mfma_f32_32x32x16_bf16 v[16:31], v[184:187], v[68:71], v[16:31]
	s_waitcnt lgkmcnt(1)
	v_mfma_f32_32x32x16_bf16 v[0:15], v[196:199], v[72:75], v[0:15]
	s_waitcnt lgkmcnt(0)
	v_mfma_f32_32x32x16_bf16 v[16:31], v[196:199], v[76:79], v[16:31]
	s_setprio 0
